# RWKV scan stage E1 (triangular inverse) hand-rewritten: pipelined LDS reads + v_pk_fma_f32, all three scan loops
# speedup vs baseline: 1.0360x; 1.0360x over previous
.LBB0_1032:
	v_cmp_gt_i32_e32 vcc, 32, v113
	v_and_b32_e32 v32, 15, v113
	s_and_saveexec_b64 s[36:37], vcc
	s_cbranch_execz .LBB0_1034
	v_lshrrev_b32_e32 v99, 4, v113
	v_mul_u32_u24_e32 v33, 0x880, v99
	v_add_u32_e32 v33, 0x2080, v33
	v_add_u32_e32 v96, 0x420, v33
	v_cmp_eq_u32_e32 vcc, 0, v32
	v_cmp_eq_u32_e64 s[10:11], 1, v32
	ds_read_b32 v116, v33 offset:4
	v_cndmask_b32_e64 v34, 0, 1.0, vcc
	ds_read2_b32 v[118:119], v33 offset0:2 offset1:3
	v_cmp_eq_u32_e32 vcc, 2, v32
	v_cndmask_b32_e64 v35, 0, 1.0, s[10:11]
	ds_read2_b32 v[120:121], v33 offset0:4 offset1:5
	v_cmp_eq_u32_e64 s[10:11], 3, v32
	v_cndmask_b32_e64 v36, 0, 1.0, vcc
	ds_read2_b32 v[122:123], v33 offset0:6 offset1:7
	v_cmp_eq_u32_e32 vcc, 4, v32
	v_cndmask_b32_e64 v37, 0, 1.0, s[10:11]
	ds_read2_b32 v[124:125], v33 offset0:8 offset1:9
	v_cmp_eq_u32_e64 s[10:11], 5, v32
	v_cndmask_b32_e64 v38, 0, 1.0, vcc
	ds_read2_b32 v[126:127], v33 offset0:10 offset1:11
	v_cmp_eq_u32_e32 vcc, 6, v32
	v_cndmask_b32_e64 v39, 0, 1.0, s[10:11]
	ds_read2_b32 v[88:89], v33 offset0:12 offset1:13
	v_cmp_eq_u32_e64 s[10:11], 7, v32
	v_cndmask_b32_e64 v40, 0, 1.0, vcc
	ds_read2_b32 v[90:91], v33 offset0:14 offset1:15
	v_cmp_eq_u32_e32 vcc, 8, v32
	v_cndmask_b32_e64 v41, 0, 1.0, s[10:11]
	ds_read2_b32 v[92:93], v33 offset0:35 offset1:36
	v_cmp_eq_u32_e64 s[10:11], 9, v32
	v_cndmask_b32_e64 v42, 0, 1.0, vcc
	ds_read2_b32 v[94:95], v33 offset0:37 offset1:38
	v_cmp_eq_u32_e32 vcc, 10, v32
	v_cndmask_b32_e64 v43, 0, 1.0, s[10:11]
	v_cmp_eq_u32_e64 s[10:11], 11, v32
	v_cndmask_b32_e64 v44, 0, 1.0, vcc
	v_cmp_eq_u32_e32 vcc, 12, v32
	v_cndmask_b32_e64 v45, 0, 1.0, s[10:11]
	v_cmp_eq_u32_e64 s[10:11], 13, v32
	v_cndmask_b32_e64 v46, 0, 1.0, vcc
	v_cmp_eq_u32_e32 vcc, 14, v32
	v_cndmask_b32_e64 v47, 0, 1.0, s[10:11]
	v_cmp_eq_u32_e64 s[10:11], 15, v32
	v_cndmask_b32_e64 v100, 0, 1.0, vcc
	s_nop 0
	v_cndmask_b32_e64 v101, 0, 1.0, s[10:11]
	s_waitcnt lgkmcnt(6)
	v_fmac_f32_e32 v35, v34, v116
	v_pk_fma_f32 v[36:37], v[34:35], v[118:119], v[36:37] op_sel:[0,0,0] op_sel_hi:[0,1,1]
	v_pk_fma_f32 v[38:39], v[34:35], v[120:121], v[38:39] op_sel:[0,0,0] op_sel_hi:[0,1,1]
	v_pk_fma_f32 v[40:41], v[34:35], v[122:123], v[40:41] op_sel:[0,0,0] op_sel_hi:[0,1,1]
	ds_read2_b32 v[116:117], v33 offset0:39 offset1:40
	ds_read2_b32 v[118:119], v33 offset0:41 offset1:42
	ds_read2_b32 v[120:121], v33 offset0:43 offset1:44
	ds_read2_b32 v[122:123], v33 offset0:45 offset1:46
	s_waitcnt lgkmcnt(6)
	v_pk_fma_f32 v[42:43], v[34:35], v[124:125], v[42:43] op_sel:[0,0,0] op_sel_hi:[0,1,1]
	v_pk_fma_f32 v[44:45], v[34:35], v[126:127], v[44:45] op_sel:[0,0,0] op_sel_hi:[0,1,1]
	v_pk_fma_f32 v[46:47], v[34:35], v[88:89], v[46:47] op_sel:[0,0,0] op_sel_hi:[0,1,1]
	v_pk_fma_f32 v[100:101], v[34:35], v[90:91], v[100:101] op_sel:[0,0,0] op_sel_hi:[0,1,1]
	ds_read2_b32 v[124:125], v33 offset0:47 offset1:48
	ds_read_b32 v126, v33 offset:276
	ds_read2_b32 v[88:89], v33 offset0:70 offset1:71
	ds_read2_b32 v[90:91], v33 offset0:72 offset1:73
	s_waitcnt lgkmcnt(6)
	v_pk_fma_f32 v[36:37], v[34:35], v[92:93], v[36:37] op_sel:[1,0,0] op_sel_hi:[1,1,1]
	v_pk_fma_f32 v[38:39], v[34:35], v[94:95], v[38:39] op_sel:[1,0,0] op_sel_hi:[1,1,1]
	v_pk_fma_f32 v[40:41], v[34:35], v[116:117], v[40:41] op_sel:[1,0,0] op_sel_hi:[1,1,1]
	v_pk_fma_f32 v[42:43], v[34:35], v[118:119], v[42:43] op_sel:[1,0,0] op_sel_hi:[1,1,1]
	ds_read2_b32 v[92:93], v33 offset0:74 offset1:75
	ds_read2_b32 v[94:95], v33 offset0:76 offset1:77
	ds_read2_b32 v[116:117], v33 offset0:78 offset1:79
	ds_read2_b32 v[118:119], v33 offset0:80 offset1:81
	s_waitcnt lgkmcnt(6)
	v_pk_fma_f32 v[44:45], v[34:35], v[120:121], v[44:45] op_sel:[1,0,0] op_sel_hi:[1,1,1]
	v_pk_fma_f32 v[46:47], v[34:35], v[122:123], v[46:47] op_sel:[1,0,0] op_sel_hi:[1,1,1]
	v_pk_fma_f32 v[100:101], v[34:35], v[124:125], v[100:101] op_sel:[1,0,0] op_sel_hi:[1,1,1]
	v_fmac_f32_e32 v37, v36, v126
	ds_read2_b32 v[120:121], v33 offset0:103 offset1:104
	ds_read2_b32 v[122:123], v33 offset0:105 offset1:106
	ds_read2_b32 v[124:125], v33 offset0:107 offset1:108
	ds_read2_b32 v[126:127], v33 offset0:109 offset1:110
	s_waitcnt lgkmcnt(6)
	v_pk_fma_f32 v[38:39], v[36:37], v[88:89], v[38:39] op_sel:[0,0,0] op_sel_hi:[0,1,1]
	v_pk_fma_f32 v[40:41], v[36:37], v[90:91], v[40:41] op_sel:[0,0,0] op_sel_hi:[0,1,1]
	v_pk_fma_f32 v[42:43], v[36:37], v[92:93], v[42:43] op_sel:[0,0,0] op_sel_hi:[0,1,1]
	v_pk_fma_f32 v[44:45], v[36:37], v[94:95], v[44:45] op_sel:[0,0,0] op_sel_hi:[0,1,1]
	ds_read2_b32 v[88:89], v33 offset0:111 offset1:112
	ds_read2_b32 v[90:91], v33 offset0:113 offset1:114
	ds_read_b32 v92, v33 offset:548
	ds_read2_b32 v[94:95], v33 offset0:138 offset1:139
	s_waitcnt lgkmcnt(6)
	v_pk_fma_f32 v[46:47], v[36:37], v[116:117], v[46:47] op_sel:[0,0,0] op_sel_hi:[0,1,1]
	v_pk_fma_f32 v[100:101], v[36:37], v[118:119], v[100:101] op_sel:[0,0,0] op_sel_hi:[0,1,1]
	v_pk_fma_f32 v[38:39], v[36:37], v[120:121], v[38:39] op_sel:[1,0,0] op_sel_hi:[1,1,1]
	v_pk_fma_f32 v[40:41], v[36:37], v[122:123], v[40:41] op_sel:[1,0,0] op_sel_hi:[1,1,1]
	ds_read2_b32 v[116:117], v33 offset0:140 offset1:141
	ds_read2_b32 v[118:119], v33 offset0:142 offset1:143
	ds_read2_b32 v[120:121], v33 offset0:144 offset1:145
	ds_read2_b32 v[122:123], v33 offset0:146 offset1:147
	s_waitcnt lgkmcnt(6)
	v_pk_fma_f32 v[42:43], v[36:37], v[124:125], v[42:43] op_sel:[1,0,0] op_sel_hi:[1,1,1]
	v_pk_fma_f32 v[44:45], v[36:37], v[126:127], v[44:45] op_sel:[1,0,0] op_sel_hi:[1,1,1]
	v_pk_fma_f32 v[46:47], v[36:37], v[88:89], v[46:47] op_sel:[1,0,0] op_sel_hi:[1,1,1]
	v_pk_fma_f32 v[100:101], v[36:37], v[90:91], v[100:101] op_sel:[1,0,0] op_sel_hi:[1,1,1]
	ds_read2_b32 v[124:125], v33 offset0:171 offset1:172
	ds_read2_b32 v[126:127], v33 offset0:173 offset1:174
	ds_read2_b32 v[88:89], v33 offset0:175 offset1:176
	ds_read2_b32 v[90:91], v33 offset0:177 offset1:178
	s_waitcnt lgkmcnt(6)
	v_fmac_f32_e32 v39, v38, v92
	v_pk_fma_f32 v[40:41], v[38:39], v[94:95], v[40:41] op_sel:[0,0,0] op_sel_hi:[0,1,1]
	v_pk_fma_f32 v[42:43], v[38:39], v[116:117], v[42:43] op_sel:[0,0,0] op_sel_hi:[0,1,1]
	v_pk_fma_f32 v[44:45], v[38:39], v[118:119], v[44:45] op_sel:[0,0,0] op_sel_hi:[0,1,1]
	ds_read2_b32 v[92:93], v33 offset0:179 offset1:180
	ds_read_b32 v94, v33 offset:820
	ds_read2_b32 v[116:117], v33 offset0:206 offset1:207
	ds_read2_b32 v[118:119], v33 offset0:208 offset1:209
	s_waitcnt lgkmcnt(6)
	v_pk_fma_f32 v[46:47], v[38:39], v[120:121], v[46:47] op_sel:[0,0,0] op_sel_hi:[0,1,1]
	v_pk_fma_f32 v[100:101], v[38:39], v[122:123], v[100:101] op_sel:[0,0,0] op_sel_hi:[0,1,1]
	v_pk_fma_f32 v[40:41], v[38:39], v[124:125], v[40:41] op_sel:[1,0,0] op_sel_hi:[1,1,1]
	v_pk_fma_f32 v[42:43], v[38:39], v[126:127], v[42:43] op_sel:[1,0,0] op_sel_hi:[1,1,1]
	ds_read2_b32 v[120:121], v33 offset0:210 offset1:211
	ds_read2_b32 v[122:123], v33 offset0:212 offset1:213
	ds_read2_b32 v[124:125], v33 offset0:239 offset1:240
	ds_read2_b32 v[126:127], v33 offset0:241 offset1:242
	s_waitcnt lgkmcnt(6)
	v_pk_fma_f32 v[44:45], v[38:39], v[88:89], v[44:45] op_sel:[1,0,0] op_sel_hi:[1,1,1]
	v_pk_fma_f32 v[46:47], v[38:39], v[90:91], v[46:47] op_sel:[1,0,0] op_sel_hi:[1,1,1]
	v_pk_fma_f32 v[100:101], v[38:39], v[92:93], v[100:101] op_sel:[1,0,0] op_sel_hi:[1,1,1]
	v_fmac_f32_e32 v41, v40, v94
	ds_read2_b32 v[88:89], v33 offset0:243 offset1:244
	ds_read2_b32 v[90:91], v33 offset0:245 offset1:246
	ds_read_b32 v92, v96 offset:36
	ds_read2_b32 v[94:95], v96 offset0:10 offset1:11
	s_waitcnt lgkmcnt(6)
	v_pk_fma_f32 v[42:43], v[40:41], v[116:117], v[42:43] op_sel:[0,0,0] op_sel_hi:[0,1,1]
	v_pk_fma_f32 v[44:45], v[40:41], v[118:119], v[44:45] op_sel:[0,0,0] op_sel_hi:[0,1,1]
	v_pk_fma_f32 v[46:47], v[40:41], v[120:121], v[46:47] op_sel:[0,0,0] op_sel_hi:[0,1,1]
	v_pk_fma_f32 v[100:101], v[40:41], v[122:123], v[100:101] op_sel:[0,0,0] op_sel_hi:[0,1,1]
	ds_read2_b32 v[116:117], v96 offset0:12 offset1:13
	ds_read2_b32 v[118:119], v96 offset0:14 offset1:15
	ds_read2_b32 v[120:121], v96 offset0:43 offset1:44
	ds_read2_b32 v[122:123], v96 offset0:45 offset1:46
	s_waitcnt lgkmcnt(6)
	v_pk_fma_f32 v[42:43], v[40:41], v[124:125], v[42:43] op_sel:[1,0,0] op_sel_hi:[1,1,1]
	v_pk_fma_f32 v[44:45], v[40:41], v[126:127], v[44:45] op_sel:[1,0,0] op_sel_hi:[1,1,1]
	v_pk_fma_f32 v[46:47], v[40:41], v[88:89], v[46:47] op_sel:[1,0,0] op_sel_hi:[1,1,1]
	v_pk_fma_f32 v[100:101], v[40:41], v[90:91], v[100:101] op_sel:[1,0,0] op_sel_hi:[1,1,1]
	ds_read2_b32 v[124:125], v96 offset0:47 offset1:48
	ds_read_b32 v126, v96 offset:308
	ds_read2_b32 v[88:89], v96 offset0:78 offset1:79
	ds_read2_b32 v[90:91], v96 offset0:80 offset1:81
	s_waitcnt lgkmcnt(6)
	v_fmac_f32_e32 v43, v42, v92
	v_pk_fma_f32 v[44:45], v[42:43], v[94:95], v[44:45] op_sel:[0,0,0] op_sel_hi:[0,1,1]
	v_pk_fma_f32 v[46:47], v[42:43], v[116:117], v[46:47] op_sel:[0,0,0] op_sel_hi:[0,1,1]
	v_pk_fma_f32 v[100:101], v[42:43], v[118:119], v[100:101] op_sel:[0,0,0] op_sel_hi:[0,1,1]
	ds_read2_b32 v[92:93], v96 offset0:111 offset1:112
	ds_read2_b32 v[94:95], v96 offset0:113 offset1:114
	ds_read_b32 v116, v96 offset:580
	ds_read2_b32 v[118:119], v96 offset0:146 offset1:147
	s_waitcnt lgkmcnt(6)
	v_pk_fma_f32 v[44:45], v[42:43], v[120:121], v[44:45] op_sel:[1,0,0] op_sel_hi:[1,1,1]
	v_pk_fma_f32 v[46:47], v[42:43], v[122:123], v[46:47] op_sel:[1,0,0] op_sel_hi:[1,1,1]
	v_pk_fma_f32 v[100:101], v[42:43], v[124:125], v[100:101] op_sel:[1,0,0] op_sel_hi:[1,1,1]
	v_fmac_f32_e32 v45, v44, v126
	ds_read2_b32 v[120:121], v96 offset0:179 offset1:180
	ds_read_b32 v122, v96 offset:852
	s_waitcnt lgkmcnt(4)
	v_pk_fma_f32 v[46:47], v[44:45], v[88:89], v[46:47] op_sel:[0,0,0] op_sel_hi:[0,1,1]
	v_pk_fma_f32 v[100:101], v[44:45], v[90:91], v[100:101] op_sel:[0,0,0] op_sel_hi:[0,1,1]
	v_pk_fma_f32 v[46:47], v[44:45], v[92:93], v[46:47] op_sel:[1,0,0] op_sel_hi:[1,1,1]
	v_pk_fma_f32 v[100:101], v[44:45], v[94:95], v[100:101] op_sel:[1,0,0] op_sel_hi:[1,1,1]
	s_waitcnt lgkmcnt(0)
	v_fmac_f32_e32 v47, v46, v116
	v_pk_fma_f32 v[100:101], v[46:47], v[118:119], v[100:101] op_sel:[0,0,0] op_sel_hi:[0,1,1]
	v_pk_fma_f32 v[100:101], v[46:47], v[120:121], v[100:101] op_sel:[1,0,0] op_sel_hi:[1,1,1]
	v_fmac_f32_e32 v101, v100, v122
	v_mul_u32_u24_e32 v33, 0x440, v99
	v_mul_u32_u24_e32 v96, 0x520, v99
	v_mul_u32_u24_e32 v99, 0x44, v32
	v_add_u32_e32 v33, v33, v99
	v_lshl_add_u32 v96, v32, 1, v96
	v_add_u32_e32 v33, 0x3100, v33
	v_add_u32_e32 v96, 0xe3c0, v96
	ds_write2_b32 v33, v34, v35 offset0:0 offset1:1
	ds_write2_b32 v33, v36, v37 offset0:2 offset1:3
	ds_write2_b32 v33, v38, v39 offset0:4 offset1:5
	ds_write2_b32 v33, v40, v41 offset0:6 offset1:7
	ds_write2_b32 v33, v42, v43 offset0:8 offset1:9
	ds_write2_b32 v33, v44, v45 offset0:10 offset1:11
	ds_write2_b32 v33, v46, v47 offset0:12 offset1:13
	ds_write2_b32 v33, v100, v101 offset0:14 offset1:15
	v_cvt_pk_bf16_f32 v116, v34, v35
	ds_write_b16 v96, v116 offset:0
	ds_write_b16_d16_hi v96, v116 offset:80
	v_cvt_pk_bf16_f32 v118, v36, v37
	ds_write_b16 v96, v118 offset:160
	ds_write_b16_d16_hi v96, v118 offset:240
	v_cvt_pk_bf16_f32 v120, v38, v39
	ds_write_b16 v96, v120 offset:320
	ds_write_b16_d16_hi v96, v120 offset:400
	v_cvt_pk_bf16_f32 v122, v40, v41
	ds_write_b16 v96, v122 offset:480
	ds_write_b16_d16_hi v96, v122 offset:560
	v_cvt_pk_bf16_f32 v124, v42, v43
	ds_write_b16 v96, v124 offset:640
	ds_write_b16_d16_hi v96, v124 offset:720
	v_cvt_pk_bf16_f32 v126, v44, v45
	ds_write_b16 v96, v126 offset:800
	ds_write_b16_d16_hi v96, v126 offset:880
	v_cvt_pk_bf16_f32 v88, v46, v47
	ds_write_b16 v96, v88 offset:960
	ds_write_b16_d16_hi v96, v88 offset:1040
	v_cvt_pk_bf16_f32 v90, v100, v101
	ds_write_b16 v96, v90 offset:1120
	ds_write_b16_d16_hi v96, v90 offset:1200

.LBB0_1212:
	v_lshrrev_b32_e32 v67, 4, v141
	v_mul_u32_u24_e32 v35, 0x880, v67
	v_add_u32_e32 v35, 0x2080, v35
	v_add_u32_e32 v50, 0x420, v35
	v_cmp_eq_u32_e32 vcc, 0, v34
	v_cmp_eq_u32_e64 s[12:13], 1, v34
	ds_read_b32 v52, v35 offset:4
	v_cndmask_b32_e64 v36, 0, 1.0, vcc
	ds_read2_b32 v[54:55], v35 offset0:2 offset1:3
	v_cmp_eq_u32_e32 vcc, 2, v34
	v_cndmask_b32_e64 v37, 0, 1.0, s[12:13]
	ds_read2_b32 v[56:57], v35 offset0:4 offset1:5
	v_cmp_eq_u32_e64 s[12:13], 3, v34
	v_cndmask_b32_e64 v38, 0, 1.0, vcc
	ds_read2_b32 v[58:59], v35 offset0:6 offset1:7
	v_cmp_eq_u32_e32 vcc, 4, v34
	v_cndmask_b32_e64 v39, 0, 1.0, s[12:13]
	ds_read2_b32 v[60:61], v35 offset0:8 offset1:9
	v_cmp_eq_u32_e64 s[12:13], 5, v34
	v_cndmask_b32_e64 v40, 0, 1.0, vcc
	ds_read2_b32 v[62:63], v35 offset0:10 offset1:11
	v_cmp_eq_u32_e32 vcc, 6, v34
	v_cndmask_b32_e64 v41, 0, 1.0, s[12:13]
	ds_read2_b32 v[64:65], v35 offset0:12 offset1:13
	v_cmp_eq_u32_e64 s[12:13], 7, v34
	v_cndmask_b32_e64 v42, 0, 1.0, vcc
	ds_read2_b32 v[72:73], v35 offset0:14 offset1:15
	v_cmp_eq_u32_e32 vcc, 8, v34
	v_cndmask_b32_e64 v43, 0, 1.0, s[12:13]
	ds_read2_b32 v[74:75], v35 offset0:35 offset1:36
	v_cmp_eq_u32_e64 s[12:13], 9, v34
	v_cndmask_b32_e64 v44, 0, 1.0, vcc
	ds_read2_b32 v[76:77], v35 offset0:37 offset1:38
	v_cmp_eq_u32_e32 vcc, 10, v34
	v_cndmask_b32_e64 v45, 0, 1.0, s[12:13]
	v_cmp_eq_u32_e64 s[12:13], 11, v34
	v_cndmask_b32_e64 v46, 0, 1.0, vcc
	v_cmp_eq_u32_e32 vcc, 12, v34
	v_cndmask_b32_e64 v47, 0, 1.0, s[12:13]
	v_cmp_eq_u32_e64 s[12:13], 13, v34
	v_cndmask_b32_e64 v48, 0, 1.0, vcc
	v_cmp_eq_u32_e32 vcc, 14, v34
	v_cndmask_b32_e64 v49, 0, 1.0, s[12:13]
	v_cmp_eq_u32_e64 s[12:13], 15, v34
	v_cndmask_b32_e64 v68, 0, 1.0, vcc
	s_nop 0
	v_cndmask_b32_e64 v69, 0, 1.0, s[12:13]
	s_waitcnt lgkmcnt(6)
	v_fmac_f32_e32 v37, v36, v52
	v_pk_fma_f32 v[38:39], v[36:37], v[54:55], v[38:39] op_sel:[0,0,0] op_sel_hi:[0,1,1]
	v_pk_fma_f32 v[40:41], v[36:37], v[56:57], v[40:41] op_sel:[0,0,0] op_sel_hi:[0,1,1]
	v_pk_fma_f32 v[42:43], v[36:37], v[58:59], v[42:43] op_sel:[0,0,0] op_sel_hi:[0,1,1]
	ds_read2_b32 v[52:53], v35 offset0:39 offset1:40
	ds_read2_b32 v[54:55], v35 offset0:41 offset1:42
	ds_read2_b32 v[56:57], v35 offset0:43 offset1:44
	ds_read2_b32 v[58:59], v35 offset0:45 offset1:46
	s_waitcnt lgkmcnt(6)
	v_pk_fma_f32 v[44:45], v[36:37], v[60:61], v[44:45] op_sel:[0,0,0] op_sel_hi:[0,1,1]
	v_pk_fma_f32 v[46:47], v[36:37], v[62:63], v[46:47] op_sel:[0,0,0] op_sel_hi:[0,1,1]
	v_pk_fma_f32 v[48:49], v[36:37], v[64:65], v[48:49] op_sel:[0,0,0] op_sel_hi:[0,1,1]
	v_pk_fma_f32 v[68:69], v[36:37], v[72:73], v[68:69] op_sel:[0,0,0] op_sel_hi:[0,1,1]
	ds_read2_b32 v[60:61], v35 offset0:47 offset1:48
	ds_read_b32 v62, v35 offset:276
	ds_read2_b32 v[64:65], v35 offset0:70 offset1:71
	ds_read2_b32 v[72:73], v35 offset0:72 offset1:73
	s_waitcnt lgkmcnt(6)
	v_pk_fma_f32 v[38:39], v[36:37], v[74:75], v[38:39] op_sel:[1,0,0] op_sel_hi:[1,1,1]
	v_pk_fma_f32 v[40:41], v[36:37], v[76:77], v[40:41] op_sel:[1,0,0] op_sel_hi:[1,1,1]
	v_pk_fma_f32 v[42:43], v[36:37], v[52:53], v[42:43] op_sel:[1,0,0] op_sel_hi:[1,1,1]
	v_pk_fma_f32 v[44:45], v[36:37], v[54:55], v[44:45] op_sel:[1,0,0] op_sel_hi:[1,1,1]
	ds_read2_b32 v[74:75], v35 offset0:74 offset1:75
	ds_read2_b32 v[76:77], v35 offset0:76 offset1:77
	ds_read2_b32 v[52:53], v35 offset0:78 offset1:79
	ds_read2_b32 v[54:55], v35 offset0:80 offset1:81
	s_waitcnt lgkmcnt(6)
	v_pk_fma_f32 v[46:47], v[36:37], v[56:57], v[46:47] op_sel:[1,0,0] op_sel_hi:[1,1,1]
	v_pk_fma_f32 v[48:49], v[36:37], v[58:59], v[48:49] op_sel:[1,0,0] op_sel_hi:[1,1,1]
	v_pk_fma_f32 v[68:69], v[36:37], v[60:61], v[68:69] op_sel:[1,0,0] op_sel_hi:[1,1,1]
	v_fmac_f32_e32 v39, v38, v62
	ds_read2_b32 v[56:57], v35 offset0:103 offset1:104
	ds_read2_b32 v[58:59], v35 offset0:105 offset1:106
	ds_read2_b32 v[60:61], v35 offset0:107 offset1:108
	ds_read2_b32 v[62:63], v35 offset0:109 offset1:110
	s_waitcnt lgkmcnt(6)
	v_pk_fma_f32 v[40:41], v[38:39], v[64:65], v[40:41] op_sel:[0,0,0] op_sel_hi:[0,1,1]
	v_pk_fma_f32 v[42:43], v[38:39], v[72:73], v[42:43] op_sel:[0,0,0] op_sel_hi:[0,1,1]
	v_pk_fma_f32 v[44:45], v[38:39], v[74:75], v[44:45] op_sel:[0,0,0] op_sel_hi:[0,1,1]
	v_pk_fma_f32 v[46:47], v[38:39], v[76:77], v[46:47] op_sel:[0,0,0] op_sel_hi:[0,1,1]
	ds_read2_b32 v[64:65], v35 offset0:111 offset1:112
	ds_read2_b32 v[72:73], v35 offset0:113 offset1:114
	ds_read_b32 v74, v35 offset:548
	ds_read2_b32 v[76:77], v35 offset0:138 offset1:139
	s_waitcnt lgkmcnt(6)
	v_pk_fma_f32 v[48:49], v[38:39], v[52:53], v[48:49] op_sel:[0,0,0] op_sel_hi:[0,1,1]
	v_pk_fma_f32 v[68:69], v[38:39], v[54:55], v[68:69] op_sel:[0,0,0] op_sel_hi:[0,1,1]
	v_pk_fma_f32 v[40:41], v[38:39], v[56:57], v[40:41] op_sel:[1,0,0] op_sel_hi:[1,1,1]
	v_pk_fma_f32 v[42:43], v[38:39], v[58:59], v[42:43] op_sel:[1,0,0] op_sel_hi:[1,1,1]
	ds_read2_b32 v[52:53], v35 offset0:140 offset1:141
	ds_read2_b32 v[54:55], v35 offset0:142 offset1:143
	ds_read2_b32 v[56:57], v35 offset0:144 offset1:145
	ds_read2_b32 v[58:59], v35 offset0:146 offset1:147
	s_waitcnt lgkmcnt(6)
	v_pk_fma_f32 v[44:45], v[38:39], v[60:61], v[44:45] op_sel:[1,0,0] op_sel_hi:[1,1,1]
	v_pk_fma_f32 v[46:47], v[38:39], v[62:63], v[46:47] op_sel:[1,0,0] op_sel_hi:[1,1,1]
	v_pk_fma_f32 v[48:49], v[38:39], v[64:65], v[48:49] op_sel:[1,0,0] op_sel_hi:[1,1,1]
	v_pk_fma_f32 v[68:69], v[38:39], v[72:73], v[68:69] op_sel:[1,0,0] op_sel_hi:[1,1,1]
	ds_read2_b32 v[60:61], v35 offset0:171 offset1:172
	ds_read2_b32 v[62:63], v35 offset0:173 offset1:174
	ds_read2_b32 v[64:65], v35 offset0:175 offset1:176
	ds_read2_b32 v[72:73], v35 offset0:177 offset1:178
	s_waitcnt lgkmcnt(6)
	v_fmac_f32_e32 v41, v40, v74
	v_pk_fma_f32 v[42:43], v[40:41], v[76:77], v[42:43] op_sel:[0,0,0] op_sel_hi:[0,1,1]
	v_pk_fma_f32 v[44:45], v[40:41], v[52:53], v[44:45] op_sel:[0,0,0] op_sel_hi:[0,1,1]
	v_pk_fma_f32 v[46:47], v[40:41], v[54:55], v[46:47] op_sel:[0,0,0] op_sel_hi:[0,1,1]
	ds_read2_b32 v[74:75], v35 offset0:179 offset1:180
	ds_read_b32 v76, v35 offset:820
	ds_read2_b32 v[52:53], v35 offset0:206 offset1:207
	ds_read2_b32 v[54:55], v35 offset0:208 offset1:209
	s_waitcnt lgkmcnt(6)
	v_pk_fma_f32 v[48:49], v[40:41], v[56:57], v[48:49] op_sel:[0,0,0] op_sel_hi:[0,1,1]
	v_pk_fma_f32 v[68:69], v[40:41], v[58:59], v[68:69] op_sel:[0,0,0] op_sel_hi:[0,1,1]
	v_pk_fma_f32 v[42:43], v[40:41], v[60:61], v[42:43] op_sel:[1,0,0] op_sel_hi:[1,1,1]
	v_pk_fma_f32 v[44:45], v[40:41], v[62:63], v[44:45] op_sel:[1,0,0] op_sel_hi:[1,1,1]
	ds_read2_b32 v[56:57], v35 offset0:210 offset1:211
	ds_read2_b32 v[58:59], v35 offset0:212 offset1:213
	ds_read2_b32 v[60:61], v35 offset0:239 offset1:240
	ds_read2_b32 v[62:63], v35 offset0:241 offset1:242
	s_waitcnt lgkmcnt(6)
	v_pk_fma_f32 v[46:47], v[40:41], v[64:65], v[46:47] op_sel:[1,0,0] op_sel_hi:[1,1,1]
	v_pk_fma_f32 v[48:49], v[40:41], v[72:73], v[48:49] op_sel:[1,0,0] op_sel_hi:[1,1,1]
	v_pk_fma_f32 v[68:69], v[40:41], v[74:75], v[68:69] op_sel:[1,0,0] op_sel_hi:[1,1,1]
	v_fmac_f32_e32 v43, v42, v76
	ds_read2_b32 v[64:65], v35 offset0:243 offset1:244
	ds_read2_b32 v[72:73], v35 offset0:245 offset1:246
	ds_read_b32 v74, v50 offset:36
	ds_read2_b32 v[76:77], v50 offset0:10 offset1:11
	s_waitcnt lgkmcnt(6)
	v_pk_fma_f32 v[44:45], v[42:43], v[52:53], v[44:45] op_sel:[0,0,0] op_sel_hi:[0,1,1]
	v_pk_fma_f32 v[46:47], v[42:43], v[54:55], v[46:47] op_sel:[0,0,0] op_sel_hi:[0,1,1]
	v_pk_fma_f32 v[48:49], v[42:43], v[56:57], v[48:49] op_sel:[0,0,0] op_sel_hi:[0,1,1]
	v_pk_fma_f32 v[68:69], v[42:43], v[58:59], v[68:69] op_sel:[0,0,0] op_sel_hi:[0,1,1]
	ds_read2_b32 v[52:53], v50 offset0:12 offset1:13
	ds_read2_b32 v[54:55], v50 offset0:14 offset1:15
	ds_read2_b32 v[56:57], v50 offset0:43 offset1:44
	ds_read2_b32 v[58:59], v50 offset0:45 offset1:46
	s_waitcnt lgkmcnt(6)
	v_pk_fma_f32 v[44:45], v[42:43], v[60:61], v[44:45] op_sel:[1,0,0] op_sel_hi:[1,1,1]
	v_pk_fma_f32 v[46:47], v[42:43], v[62:63], v[46:47] op_sel:[1,0,0] op_sel_hi:[1,1,1]
	v_pk_fma_f32 v[48:49], v[42:43], v[64:65], v[48:49] op_sel:[1,0,0] op_sel_hi:[1,1,1]
	v_pk_fma_f32 v[68:69], v[42:43], v[72:73], v[68:69] op_sel:[1,0,0] op_sel_hi:[1,1,1]
	ds_read2_b32 v[60:61], v50 offset0:47 offset1:48
	ds_read_b32 v62, v50 offset:308
	ds_read2_b32 v[64:65], v50 offset0:78 offset1:79
	ds_read2_b32 v[72:73], v50 offset0:80 offset1:81
	s_waitcnt lgkmcnt(6)
	v_fmac_f32_e32 v45, v44, v74
	v_pk_fma_f32 v[46:47], v[44:45], v[76:77], v[46:47] op_sel:[0,0,0] op_sel_hi:[0,1,1]
	v_pk_fma_f32 v[48:49], v[44:45], v[52:53], v[48:49] op_sel:[0,0,0] op_sel_hi:[0,1,1]
	v_pk_fma_f32 v[68:69], v[44:45], v[54:55], v[68:69] op_sel:[0,0,0] op_sel_hi:[0,1,1]
	ds_read2_b32 v[74:75], v50 offset0:111 offset1:112
	ds_read2_b32 v[76:77], v50 offset0:113 offset1:114
	ds_read_b32 v52, v50 offset:580
	ds_read2_b32 v[54:55], v50 offset0:146 offset1:147
	s_waitcnt lgkmcnt(6)
	v_pk_fma_f32 v[46:47], v[44:45], v[56:57], v[46:47] op_sel:[1,0,0] op_sel_hi:[1,1,1]
	v_pk_fma_f32 v[48:49], v[44:45], v[58:59], v[48:49] op_sel:[1,0,0] op_sel_hi:[1,1,1]
	v_pk_fma_f32 v[68:69], v[44:45], v[60:61], v[68:69] op_sel:[1,0,0] op_sel_hi:[1,1,1]
	v_fmac_f32_e32 v47, v46, v62
	ds_read2_b32 v[56:57], v50 offset0:179 offset1:180
	ds_read_b32 v58, v50 offset:852
	s_waitcnt lgkmcnt(4)
	v_pk_fma_f32 v[48:49], v[46:47], v[64:65], v[48:49] op_sel:[0,0,0] op_sel_hi:[0,1,1]
	v_pk_fma_f32 v[68:69], v[46:47], v[72:73], v[68:69] op_sel:[0,0,0] op_sel_hi:[0,1,1]
	v_pk_fma_f32 v[48:49], v[46:47], v[74:75], v[48:49] op_sel:[1,0,0] op_sel_hi:[1,1,1]
	v_pk_fma_f32 v[68:69], v[46:47], v[76:77], v[68:69] op_sel:[1,0,0] op_sel_hi:[1,1,1]
	s_waitcnt lgkmcnt(0)
	v_fmac_f32_e32 v49, v48, v52
	v_pk_fma_f32 v[68:69], v[48:49], v[54:55], v[68:69] op_sel:[0,0,0] op_sel_hi:[0,1,1]
	v_pk_fma_f32 v[68:69], v[48:49], v[56:57], v[68:69] op_sel:[1,0,0] op_sel_hi:[1,1,1]
	v_fmac_f32_e32 v69, v68, v58
	v_mul_u32_u24_e32 v35, 0x440, v67
	v_mul_u32_u24_e32 v50, 0x520, v67
	v_mul_u32_u24_e32 v67, 0x44, v34
	v_add_u32_e32 v35, v35, v67
	v_lshl_add_u32 v50, v34, 1, v50
	v_add_u32_e32 v35, 0x3100, v35
	v_add_u32_e32 v50, 0xe3c0, v50
	ds_write2_b32 v35, v36, v37 offset0:0 offset1:1
	ds_write2_b32 v35, v38, v39 offset0:2 offset1:3
	ds_write2_b32 v35, v40, v41 offset0:4 offset1:5
	ds_write2_b32 v35, v42, v43 offset0:6 offset1:7
	ds_write2_b32 v35, v44, v45 offset0:8 offset1:9
	ds_write2_b32 v35, v46, v47 offset0:10 offset1:11
	ds_write2_b32 v35, v48, v49 offset0:12 offset1:13
	ds_write2_b32 v35, v68, v69 offset0:14 offset1:15
	v_cvt_pk_bf16_f32 v52, v36, v37
	ds_write_b16 v50, v52 offset:0
	ds_write_b16_d16_hi v50, v52 offset:80
	v_cvt_pk_bf16_f32 v54, v38, v39
	ds_write_b16 v50, v54 offset:160
	ds_write_b16_d16_hi v50, v54 offset:240
	v_cvt_pk_bf16_f32 v56, v40, v41
	ds_write_b16 v50, v56 offset:320
	ds_write_b16_d16_hi v50, v56 offset:400
	v_cvt_pk_bf16_f32 v58, v42, v43
	ds_write_b16 v50, v58 offset:480
	ds_write_b16_d16_hi v50, v58 offset:560
	v_cvt_pk_bf16_f32 v60, v44, v45
	ds_write_b16 v50, v60 offset:640
	ds_write_b16_d16_hi v50, v60 offset:720
	v_cvt_pk_bf16_f32 v62, v46, v47
	ds_write_b16 v50, v62 offset:800
	ds_write_b16_d16_hi v50, v62 offset:880
	v_cvt_pk_bf16_f32 v64, v48, v49
	ds_write_b16 v50, v64 offset:960
	ds_write_b16_d16_hi v50, v64 offset:1040
	v_cvt_pk_bf16_f32 v72, v68, v69
	ds_write_b16 v50, v72 offset:1120
	ds_write_b16_d16_hi v50, v72 offset:1200
